# loop-edge edit: flash-attention loop latches rotated to a single conditional back-branch (running-max copy made unconditional), on top of mid-stage-barrier GEMM loops
# baseline (speedup 1.0000x reference)
.LBB0_781:
	v_fma_f32 v80, v80, s59, -v141
	v_exp_f32_e32 v80, v80
	v_fma_f32 v81, v81, s59, -v141
	v_exp_f32_e32 v81, v81
	v_fma_f32 v82, v82, s59, -v141
	v_exp_f32_e32 v82, v82
	v_add_f32_e32 v149, 0, v80
	v_fma_f32 v83, v83, s59, -v141
	v_exp_f32_e32 v83, v83
	v_add_f32_e32 v149, v81, v149
	v_fma_f32 v84, v84, s59, -v141
	v_exp_f32_e32 v84, v84
	v_add_f32_e32 v149, v82, v149
	v_add_f32_e32 v149, v83, v149
	v_fma_f32 v85, v85, s59, -v141
	v_exp_f32_e32 v85, v85
	v_fma_f32 v86, v86, s59, -v141
	v_exp_f32_e32 v86, v86
	v_add_f32_e32 v149, v84, v149
	v_fma_f32 v87, v87, s59, -v141
	v_exp_f32_e32 v87, v87
	v_add_f32_e32 v149, v85, v149
	v_add_f32_e32 v149, v86, v149
	v_add_f32_e32 v149, v87, v149
	v_cvt_pk_bf16_f32 v212, v80, v81
	v_cvt_pk_bf16_f32 v213, v82, v83
	v_cvt_pk_bf16_f32 v214, v84, v85
	v_cvt_pk_bf16_f32 v215, v86, v87
	s_nop 1
	v_mfma_f32_32x32x16_bf16 v[48:63], v[162:165], v[212:215], v[48:63]
	ds_read_b128 v[162:165], v148 offset:9280
	v_fma_f32 v88, v88, s59, -v141
	v_exp_f32_e32 v88, v88
	v_fma_f32 v89, v89, s59, -v141
	v_exp_f32_e32 v89, v89
	v_fma_f32 v90, v90, s59, -v141
	v_exp_f32_e32 v90, v90
	v_add_f32_e32 v149, v88, v149
	v_mfma_f32_32x32x16_bf16 v[32:47], v[166:169], v[212:215], v[32:47]
	ds_read_b128 v[166:169], v148 offset:13888
	v_fma_f32 v91, v91, s59, -v141
	v_exp_f32_e32 v91, v91
	v_add_f32_e32 v149, v89, v149
	v_fma_f32 v92, v92, s59, -v141
	v_exp_f32_e32 v92, v92
	v_add_f32_e32 v149, v90, v149
	v_add_f32_e32 v149, v91, v149
	v_mfma_f32_32x32x16_bf16 v[16:31], v[170:173], v[212:215], v[16:31]
	ds_read_b128 v[170:173], v148 offset:18496
	v_fma_f32 v93, v93, s59, -v141
	v_exp_f32_e32 v93, v93
	v_fma_f32 v94, v94, s59, -v141
	v_exp_f32_e32 v94, v94
	v_add_f32_e32 v149, v92, v149
	v_fma_f32 v95, v95, s59, -v141
	v_exp_f32_e32 v95, v95
	v_mfma_f32_32x32x16_bf16 v[0:15], v[174:177], v[212:215], v[0:15]
	ds_read_b128 v[174:177], v148 offset:23104
	v_add_f32_e32 v149, v93, v149
	v_add_f32_e32 v149, v94, v149
	v_add_f32_e32 v149, v95, v149
	v_cvt_pk_bf16_f32 v216, v88, v89
	v_cvt_pk_bf16_f32 v217, v90, v91
	v_cvt_pk_bf16_f32 v218, v92, v93
	v_cvt_pk_bf16_f32 v219, v94, v95
	s_nop 1
	v_mfma_f32_32x32x16_bf16 v[48:63], v[178:181], v[216:219], v[48:63]
	ds_read_b128 v[178:181], v148 offset:9312
	v_fma_f32 v64, v64, s59, -v141
	v_exp_f32_e32 v64, v64
	v_fma_f32 v65, v65, s59, -v141
	v_exp_f32_e32 v65, v65
	v_fma_f32 v66, v66, s59, -v141
	v_exp_f32_e32 v66, v66
	v_add_f32_e32 v149, v64, v149
	v_mfma_f32_32x32x16_bf16 v[32:47], v[200:203], v[216:219], v[32:47]
	ds_read_b128 v[200:203], v148 offset:13920
	v_fma_f32 v67, v67, s59, -v141
	v_exp_f32_e32 v67, v67
	v_add_f32_e32 v149, v65, v149
	v_fma_f32 v68, v68, s59, -v141
	v_exp_f32_e32 v68, v68
	v_add_f32_e32 v149, v66, v149
	v_add_f32_e32 v149, v67, v149
	v_mfma_f32_32x32x16_bf16 v[16:31], v[204:207], v[216:219], v[16:31]
	ds_read_b128 v[204:207], v148 offset:18528
	v_fma_f32 v69, v69, s59, -v141
	v_exp_f32_e32 v69, v69
	v_fma_f32 v70, v70, s59, -v141
	v_exp_f32_e32 v70, v70
	v_add_f32_e32 v149, v68, v149
	v_fma_f32 v71, v71, s59, -v141
	v_exp_f32_e32 v71, v71
	v_mfma_f32_32x32x16_bf16 v[0:15], v[208:211], v[216:219], v[0:15]
	ds_read_b128 v[208:211], v148 offset:23136
	v_add_f32_e32 v149, v69, v149
	v_add_f32_e32 v149, v70, v149
	v_add_f32_e32 v149, v71, v149
	v_cvt_pk_bf16_f32 v246, v64, v65
	v_cvt_pk_bf16_f32 v247, v66, v67
	v_cvt_pk_bf16_f32 v248, v68, v69
	v_cvt_pk_bf16_f32 v249, v70, v71
	s_nop 1
	s_waitcnt lgkmcnt(7)
	v_mfma_f32_32x32x16_bf16 v[48:63], v[162:165], v[246:249], v[48:63]
	v_fma_f32 v72, v72, s59, -v141
	v_exp_f32_e32 v72, v72
	v_fma_f32 v73, v73, s59, -v141
	v_exp_f32_e32 v73, v73
	v_fma_f32 v74, v74, s59, -v141
	v_exp_f32_e32 v74, v74
	v_add_f32_e32 v149, v72, v149
	s_waitcnt lgkmcnt(6)
	v_mfma_f32_32x32x16_bf16 v[32:47], v[166:169], v[246:249], v[32:47]
	v_fma_f32 v75, v75, s59, -v141
	v_exp_f32_e32 v75, v75
	v_add_f32_e32 v149, v73, v149
	v_fma_f32 v76, v76, s59, -v141
	v_exp_f32_e32 v76, v76
	v_add_f32_e32 v149, v74, v149
	v_add_f32_e32 v149, v75, v149
	s_waitcnt lgkmcnt(5)
	v_mfma_f32_32x32x16_bf16 v[16:31], v[170:173], v[246:249], v[16:31]
	v_fma_f32 v77, v77, s59, -v141
	v_exp_f32_e32 v77, v77
	v_fma_f32 v78, v78, s59, -v141
	v_exp_f32_e32 v78, v78
	v_add_f32_e32 v149, v76, v149
	v_fma_f32 v79, v79, s59, -v141
	v_exp_f32_e32 v79, v79
	s_waitcnt lgkmcnt(4)
	v_mfma_f32_32x32x16_bf16 v[0:15], v[174:177], v[246:249], v[0:15]
	v_add_f32_e32 v149, v77, v149
	v_add_f32_e32 v149, v78, v149
	v_add_f32_e32 v149, v79, v149
	v_cvt_pk_bf16_f32 v212, v72, v73
	v_cvt_pk_bf16_f32 v213, v74, v75
	v_cvt_pk_bf16_f32 v214, v76, v77
	v_cvt_pk_bf16_f32 v215, v78, v79
	s_nop 1
	s_waitcnt lgkmcnt(3)
	v_mfma_f32_32x32x16_bf16 v[48:63], v[178:181], v[212:215], v[48:63]
	v_add_f32_e32 v143, v149, v143
	s_add_u32 s48, s48, 0x10000
	s_addc_u32 s49, s49, 0
	s_waitcnt lgkmcnt(2)
	v_mfma_f32_32x32x16_bf16 v[32:47], v[200:203], v[212:215], v[32:47]
	v_lshl_add_u64 v[146:147], v[146:147], 0, s[16:17]
	s_cmp_eq_u32 s48, 0x470000
	s_waitcnt lgkmcnt(1)
	v_mfma_f32_32x32x16_bf16 v[16:31], v[204:207], v[212:215], v[16:31]
	s_waitcnt lgkmcnt(0)
	s_barrier
	v_mfma_f32_32x32x16_bf16 v[0:15], v[208:211], v[212:215], v[0:15]
	v_mov_b32_e32 v149, v141
	s_cbranch_scc0 .LBB0_779

.LBB0_788:
	v_fma_f32 v80, v80, s59, -v152
	v_exp_f32_e32 v80, v80
	v_fma_f32 v81, v81, s59, -v152
	v_exp_f32_e32 v81, v81
	v_fma_f32 v82, v82, s59, -v152
	v_exp_f32_e32 v82, v82
	v_add_f32_e32 v153, 0, v80
	v_fma_f32 v83, v83, s59, -v152
	v_exp_f32_e32 v83, v83
	v_add_f32_e32 v153, v81, v153
	v_fma_f32 v84, v84, s59, -v152
	v_exp_f32_e32 v84, v84
	v_add_f32_e32 v153, v82, v153
	v_add_f32_e32 v153, v83, v153
	v_fma_f32 v85, v85, s59, -v152
	v_exp_f32_e32 v85, v85
	v_fma_f32 v86, v86, s59, -v152
	v_exp_f32_e32 v86, v86
	v_add_f32_e32 v153, v84, v153
	v_fma_f32 v87, v87, s59, -v152
	v_exp_f32_e32 v87, v87
	v_add_f32_e32 v153, v85, v153
	v_add_f32_e32 v153, v86, v153
	v_add_f32_e32 v153, v87, v153
	v_cvt_pk_bf16_f32 v212, v80, v81
	v_cvt_pk_bf16_f32 v213, v82, v83
	v_cvt_pk_bf16_f32 v214, v84, v85
	v_cvt_pk_bf16_f32 v215, v86, v87
	s_nop 1
	v_mfma_f32_32x32x16_bf16 v[48:63], v[162:165], v[212:215], v[48:63]
	ds_read_b128 v[162:165], v143 offset:9280
	v_fma_f32 v88, v88, s59, -v152
	v_exp_f32_e32 v88, v88
	v_fma_f32 v89, v89, s59, -v152
	v_exp_f32_e32 v89, v89
	v_fma_f32 v90, v90, s59, -v152
	v_exp_f32_e32 v90, v90
	v_add_f32_e32 v153, v88, v153
	v_mfma_f32_32x32x16_bf16 v[32:47], v[166:169], v[212:215], v[32:47]
	ds_read_b128 v[166:169], v143 offset:13888
	v_fma_f32 v91, v91, s59, -v152
	v_exp_f32_e32 v91, v91
	v_add_f32_e32 v153, v89, v153
	v_fma_f32 v92, v92, s59, -v152
	v_exp_f32_e32 v92, v92
	v_add_f32_e32 v153, v90, v153
	v_add_f32_e32 v153, v91, v153
	v_mfma_f32_32x32x16_bf16 v[16:31], v[170:173], v[212:215], v[16:31]
	ds_read_b128 v[170:173], v143 offset:18496
	v_fma_f32 v93, v93, s59, -v152
	v_exp_f32_e32 v93, v93
	v_fma_f32 v94, v94, s59, -v152
	v_exp_f32_e32 v94, v94
	v_add_f32_e32 v153, v92, v153
	v_fma_f32 v95, v95, s59, -v152
	v_exp_f32_e32 v95, v95
	v_mfma_f32_32x32x16_bf16 v[0:15], v[174:177], v[212:215], v[0:15]
	ds_read_b128 v[174:177], v143 offset:23104
	v_add_f32_e32 v153, v93, v153
	v_add_f32_e32 v153, v94, v153
	v_add_f32_e32 v153, v95, v153
	v_cvt_pk_bf16_f32 v216, v88, v89
	v_cvt_pk_bf16_f32 v217, v90, v91
	v_cvt_pk_bf16_f32 v218, v92, v93
	v_cvt_pk_bf16_f32 v219, v94, v95
	s_nop 1
	v_mfma_f32_32x32x16_bf16 v[48:63], v[178:181], v[216:219], v[48:63]
	ds_read_b128 v[178:181], v143 offset:9312
	v_fma_f32 v64, v64, s59, -v152
	v_exp_f32_e32 v64, v64
	v_fma_f32 v65, v65, s59, -v152
	v_exp_f32_e32 v65, v65
	v_fma_f32 v66, v66, s59, -v152
	v_exp_f32_e32 v66, v66
	v_add_f32_e32 v153, v64, v153
	v_mfma_f32_32x32x16_bf16 v[32:47], v[200:203], v[216:219], v[32:47]
	ds_read_b128 v[200:203], v143 offset:13920
	v_fma_f32 v67, v67, s59, -v152
	v_exp_f32_e32 v67, v67
	v_add_f32_e32 v153, v65, v153
	v_fma_f32 v68, v68, s59, -v152
	v_exp_f32_e32 v68, v68
	v_add_f32_e32 v153, v66, v153
	v_add_f32_e32 v153, v67, v153
	v_mfma_f32_32x32x16_bf16 v[16:31], v[204:207], v[216:219], v[16:31]
	ds_read_b128 v[204:207], v143 offset:18528
	v_fma_f32 v69, v69, s59, -v152
	v_exp_f32_e32 v69, v69
	v_fma_f32 v70, v70, s59, -v152
	v_exp_f32_e32 v70, v70
	v_add_f32_e32 v153, v68, v153
	v_fma_f32 v71, v71, s59, -v152
	v_exp_f32_e32 v71, v71
	v_mfma_f32_32x32x16_bf16 v[0:15], v[208:211], v[216:219], v[0:15]
	ds_read_b128 v[208:211], v143 offset:23136
	v_add_f32_e32 v153, v69, v153
	v_add_f32_e32 v153, v70, v153
	v_add_f32_e32 v153, v71, v153
	v_cvt_pk_bf16_f32 v246, v64, v65
	v_cvt_pk_bf16_f32 v247, v66, v67
	v_cvt_pk_bf16_f32 v248, v68, v69
	v_cvt_pk_bf16_f32 v249, v70, v71
	s_nop 1
	s_waitcnt lgkmcnt(7)
	v_mfma_f32_32x32x16_bf16 v[48:63], v[162:165], v[246:249], v[48:63]
	v_fma_f32 v72, v72, s59, -v152
	v_exp_f32_e32 v72, v72
	v_fma_f32 v73, v73, s59, -v152
	v_exp_f32_e32 v73, v73
	v_fma_f32 v74, v74, s59, -v152
	v_exp_f32_e32 v74, v74
	v_add_f32_e32 v153, v72, v153
	s_waitcnt lgkmcnt(6)
	v_mfma_f32_32x32x16_bf16 v[32:47], v[166:169], v[246:249], v[32:47]
	v_fma_f32 v75, v75, s59, -v152
	v_exp_f32_e32 v75, v75
	v_add_f32_e32 v153, v73, v153
	v_fma_f32 v76, v76, s59, -v152
	v_exp_f32_e32 v76, v76
	v_add_f32_e32 v153, v74, v153
	v_add_f32_e32 v153, v75, v153
	s_waitcnt lgkmcnt(5)
	v_mfma_f32_32x32x16_bf16 v[16:31], v[170:173], v[246:249], v[16:31]
	v_fma_f32 v77, v77, s59, -v152
	v_exp_f32_e32 v77, v77
	v_fma_f32 v78, v78, s59, -v152
	v_exp_f32_e32 v78, v78
	v_add_f32_e32 v153, v76, v153
	v_fma_f32 v79, v79, s59, -v152
	v_exp_f32_e32 v79, v79
	s_waitcnt lgkmcnt(4)
	v_mfma_f32_32x32x16_bf16 v[0:15], v[174:177], v[246:249], v[0:15]
	v_add_f32_e32 v153, v77, v153
	v_add_f32_e32 v153, v78, v153
	v_add_f32_e32 v153, v79, v153
	v_cvt_pk_bf16_f32 v212, v72, v73
	v_cvt_pk_bf16_f32 v213, v74, v75
	v_cvt_pk_bf16_f32 v214, v76, v77
	v_cvt_pk_bf16_f32 v215, v78, v79
	s_nop 1
	s_waitcnt lgkmcnt(3)
	v_mfma_f32_32x32x16_bf16 v[48:63], v[178:181], v[212:215], v[48:63]
	v_add_f32_e32 v137, v153, v137
	s_add_u32 s4, s4, 0x10000
	s_addc_u32 s5, s5, 0
	s_waitcnt lgkmcnt(2)
	v_mfma_f32_32x32x16_bf16 v[32:47], v[200:203], v[212:215], v[32:47]
	v_lshl_add_u64 v[148:149], v[148:149], 0, s[16:17]
	s_cmp_eq_u32 s4, 0x470000
	s_waitcnt lgkmcnt(1)
	v_mfma_f32_32x32x16_bf16 v[16:31], v[204:207], v[212:215], v[16:31]
	s_waitcnt lgkmcnt(0)
	s_barrier
	v_mfma_f32_32x32x16_bf16 v[0:15], v[208:211], v[212:215], v[0:15]
	v_mov_b32_e32 v153, v152
	s_cbranch_scc0 .LBB0_786

.LBB0_798:
	v_fma_f32 v64, v64, s37, -v205
	v_exp_f32_e32 v64, v64
	v_fma_f32 v65, v65, s37, -v205
	v_exp_f32_e32 v65, v65
	v_fma_f32 v66, v66, s37, -v205
	v_exp_f32_e32 v66, v66
	v_add_f32_e32 v210, 0, v64
	v_fma_f32 v67, v67, s37, -v205
	v_exp_f32_e32 v67, v67
	v_add_f32_e32 v210, v65, v210
	v_fma_f32 v68, v68, s37, -v205
	v_exp_f32_e32 v68, v68
	v_add_f32_e32 v210, v66, v210
	v_add_f32_e32 v210, v67, v210
	v_fma_f32 v69, v69, s37, -v205
	v_exp_f32_e32 v69, v69
	v_fma_f32 v70, v70, s37, -v205
	v_exp_f32_e32 v70, v70
	v_add_f32_e32 v210, v68, v210
	v_fma_f32 v71, v71, s37, -v205
	v_exp_f32_e32 v71, v71
	v_add_f32_e32 v210, v69, v210
	v_add_f32_e32 v210, v70, v210
	v_add_f32_e32 v210, v71, v210
	v_cvt_pk_bf16_f32 v64, v64, v65
	v_cvt_pk_bf16_f32 v65, v66, v67
	v_cvt_pk_bf16_f32 v66, v68, v69
	v_cvt_pk_bf16_f32 v67, v70, v71
	s_nop 1
	v_mfma_f32_32x32x16_bf16 v[48:63], v[212:215], v[64:67], v[48:63]
	ds_read_b128 v[212:215], v190 offset:39424
	v_fma_f32 v72, v72, s37, -v205
	v_exp_f32_e32 v72, v72
	v_fma_f32 v73, v73, s37, -v205
	v_exp_f32_e32 v73, v73
	v_fma_f32 v74, v74, s37, -v205
	v_exp_f32_e32 v74, v74
	v_add_f32_e32 v210, v72, v210
	v_mfma_f32_32x32x16_bf16 v[32:47], v[216:219], v[64:67], v[32:47]
	ds_read_b128 v[216:219], v190 offset:25632
	v_fma_f32 v75, v75, s37, -v205
	v_exp_f32_e32 v75, v75
	v_add_f32_e32 v210, v73, v210
	v_fma_f32 v76, v76, s37, -v205
	v_exp_f32_e32 v76, v76
	v_add_f32_e32 v210, v74, v210
	v_add_f32_e32 v210, v75, v210
	v_mfma_f32_32x32x16_bf16 v[16:31], v[246:249], v[64:67], v[16:31]
	ds_read_b128 v[246:249], v190 offset:30240
	v_fma_f32 v77, v77, s37, -v205
	v_exp_f32_e32 v77, v77
	v_fma_f32 v78, v78, s37, -v205
	v_exp_f32_e32 v78, v78
	v_add_f32_e32 v210, v76, v210
	v_fma_f32 v79, v79, s37, -v205
	v_exp_f32_e32 v79, v79
	s_waitcnt lgkmcnt(2)
	v_mfma_f32_32x32x16_bf16 v[0:15], v[212:215], v[64:67], v[0:15]
	ds_read_b128 v[212:215], v190 offset:34848
	v_add_f32_e32 v210, v77, v210
	v_add_f32_e32 v210, v78, v210
	v_add_f32_e32 v210, v79, v210
	v_cvt_pk_bf16_f32 v72, v72, v73
	v_cvt_pk_bf16_f32 v73, v74, v75
	v_cvt_pk_bf16_f32 v74, v76, v77
	v_cvt_pk_bf16_f32 v75, v78, v79
	s_nop 1
	s_waitcnt lgkmcnt(2)
	v_mfma_f32_32x32x16_bf16 v[48:63], v[216:219], v[72:75], v[48:63]
	ds_read_b128 v[216:219], v190 offset:39456
	v_fma_f32 v80, v80, s37, -v205
	v_exp_f32_e32 v80, v80
	v_fma_f32 v81, v81, s37, -v205
	v_exp_f32_e32 v81, v81
	v_fma_f32 v82, v82, s37, -v205
	v_exp_f32_e32 v82, v82
	v_add_f32_e32 v210, v80, v210
	s_waitcnt lgkmcnt(2)
	v_mfma_f32_32x32x16_bf16 v[32:47], v[246:249], v[72:75], v[32:47]
	ds_read_b128 v[246:249], v190 offset:25664
	v_fma_f32 v83, v83, s37, -v205
	v_exp_f32_e32 v83, v83
	v_add_f32_e32 v210, v81, v210
	v_fma_f32 v84, v84, s37, -v205
	v_exp_f32_e32 v84, v84
	v_add_f32_e32 v210, v82, v210
	v_add_f32_e32 v210, v83, v210
	s_waitcnt lgkmcnt(2)
	v_mfma_f32_32x32x16_bf16 v[16:31], v[212:215], v[72:75], v[16:31]
	ds_read_b128 v[212:215], v190 offset:30272
	v_fma_f32 v85, v85, s37, -v205
	v_exp_f32_e32 v85, v85
	v_fma_f32 v86, v86, s37, -v205
	v_exp_f32_e32 v86, v86
	v_add_f32_e32 v210, v84, v210
	v_fma_f32 v87, v87, s37, -v205
	v_exp_f32_e32 v87, v87
	s_waitcnt lgkmcnt(2)
	v_mfma_f32_32x32x16_bf16 v[0:15], v[216:219], v[72:75], v[0:15]
	ds_read_b128 v[216:219], v190 offset:34880
	v_add_f32_e32 v210, v85, v210
	v_add_f32_e32 v210, v86, v210
	v_add_f32_e32 v210, v87, v210
	v_cvt_pk_bf16_f32 v80, v80, v81
	v_cvt_pk_bf16_f32 v81, v82, v83
	v_cvt_pk_bf16_f32 v82, v84, v85
	v_cvt_pk_bf16_f32 v83, v86, v87
	s_nop 1
	s_waitcnt lgkmcnt(2)
	v_mfma_f32_32x32x16_bf16 v[48:63], v[246:249], v[80:83], v[48:63]
	ds_read_b128 v[246:249], v190 offset:39488
	v_fma_f32 v88, v88, s37, -v205
	v_exp_f32_e32 v88, v88
	v_fma_f32 v89, v89, s37, -v205
	v_exp_f32_e32 v89, v89
	v_fma_f32 v90, v90, s37, -v205
	v_exp_f32_e32 v90, v90
	v_add_f32_e32 v210, v88, v210
	s_waitcnt lgkmcnt(2)
	v_mfma_f32_32x32x16_bf16 v[32:47], v[212:215], v[80:83], v[32:47]
	ds_read_b128 v[212:215], v190 offset:25696
	v_fma_f32 v91, v91, s37, -v205
	v_exp_f32_e32 v91, v91
	v_add_f32_e32 v210, v89, v210
	v_fma_f32 v92, v92, s37, -v205
	v_exp_f32_e32 v92, v92
	v_add_f32_e32 v210, v90, v210
	v_add_f32_e32 v210, v91, v210
	s_waitcnt lgkmcnt(2)
	v_mfma_f32_32x32x16_bf16 v[16:31], v[216:219], v[80:83], v[16:31]
	ds_read_b128 v[216:219], v190 offset:30304
	v_fma_f32 v93, v93, s37, -v205
	v_exp_f32_e32 v93, v93
	v_fma_f32 v94, v94, s37, -v205
	v_exp_f32_e32 v94, v94
	v_add_f32_e32 v210, v92, v210
	v_fma_f32 v95, v95, s37, -v205
	v_exp_f32_e32 v95, v95
	s_waitcnt lgkmcnt(2)
	v_mfma_f32_32x32x16_bf16 v[0:15], v[246:249], v[80:83], v[0:15]
	ds_read_b128 v[246:249], v190 offset:34912
	v_add_f32_e32 v210, v93, v210
	v_add_f32_e32 v210, v94, v210
	v_add_f32_e32 v210, v95, v210
	v_cvt_pk_bf16_f32 v88, v88, v89
	v_cvt_pk_bf16_f32 v89, v90, v91
	v_cvt_pk_bf16_f32 v90, v92, v93
	v_cvt_pk_bf16_f32 v91, v94, v95
	s_nop 1
	s_waitcnt lgkmcnt(2)
	v_mfma_f32_32x32x16_bf16 v[48:63], v[212:215], v[88:91], v[48:63]
	ds_read_b128 v[212:215], v190 offset:39520
	v_add_f32_e32 v201, v210, v201
	s_add_u32 s4, s4, 0x80
	s_addc_u32 s5, s5, 0
	s_waitcnt lgkmcnt(2)
	v_mfma_f32_32x32x16_bf16 v[32:47], v[216:219], v[88:91], v[32:47]
	s_mov_b64 s[18:19], 0x18000
	v_lshl_add_u64 v[208:209], v[208:209], 0, s[18:19]
	s_cmpk_eq_i32 s4, 0x2380
	s_waitcnt lgkmcnt(1)
	v_mfma_f32_32x32x16_bf16 v[16:31], v[246:249], v[88:91], v[16:31]
	s_waitcnt lgkmcnt(0)
	s_barrier
	v_mfma_f32_32x32x16_bf16 v[0:15], v[212:215], v[88:91], v[0:15]
	v_mov_b32_e32 v210, v205
	s_cbranch_scc0 .LBB0_796
